# W_out residual epilogues (both tails): base tile read six row-pair groups ahead into rotating registers with counted waits (was one load pair + vmcnt(0) per group): more reads in flight per wave
# speedup vs baseline: 1.0029x; 1.0029x over previous
.LBB0_1387:
	s_lshl_b32 s6, s74, 8
	v_add_u32_e32 v140, s6, v159
	v_ashrrev_i32_e32 v141, 31, v140
	v_lshl_or_b32 v138, s8, 8, v163
	v_lshlrev_b32_e32 v202, 12, v140
	v_lshl_add_u32 v202, v138, 2, v202
	v_lshlrev_b64 v[142:143], 12, v[140:141]
	v_ashrrev_i32_e32 v139, 31, v138
	v_lshl_add_u64 v[142:143], s[26:27], 0, v[142:143]
	v_lshl_add_u64 v[144:145], v[138:139], 2, v[142:143]
	s_add_u32 s98, s26, 0x0
	s_addc_u32 s99, s27, 0
	global_load_dwordx4 v[184:187], v202, s[98:99]
	global_load_dwordx4 v[188:191], v202, s[98:99] offset:16
	s_add_u32 s98, s26, 0x0
	s_addc_u32 s99, s27, 0
	global_load_dwordx4 v[192:195], v202, s[98:99] offset:512
	global_load_dwordx4 v[196:199], v202, s[98:99] offset:528
	s_add_u32 s98, s26, 0x10000
	s_addc_u32 s99, s27, 0
	global_load_dwordx4 v[212:215], v202, s[98:99]
	global_load_dwordx4 v[216:219], v202, s[98:99] offset:16
	s_add_u32 s98, s26, 0x10000
	s_addc_u32 s99, s27, 0
	global_load_dwordx4 v[220:223], v202, s[98:99] offset:512
	global_load_dwordx4 v[224:227], v202, s[98:99] offset:528
	s_add_u32 s98, s26, 0x20000
	s_addc_u32 s99, s27, 0
	global_load_dwordx4 v[228:231], v202, s[98:99]
	global_load_dwordx4 v[232:235], v202, s[98:99] offset:16
	s_add_u32 s98, s26, 0x20000
	s_addc_u32 s99, s27, 0
	global_load_dwordx4 v[236:239], v202, s[98:99] offset:512
	global_load_dwordx4 v[240:243], v202, s[98:99] offset:528
	s_add_u32 s98, s26, 0x30000
	s_addc_u32 s99, s27, 0
	global_load_dwordx4 v[244:247], v202, s[98:99]
	global_load_dwordx4 v[248:251], v202, s[98:99] offset:16
	s_add_i32 s7, s6, 0xfffff500
	s_cmp_lt_i32 s74, 32
	v_cndmask_b32_e64 v142, 0, 1, s[24:25]
	s_cselect_b32 s6, s6, s7
	v_cmp_ne_u32_e64 s[8:9], 1, v142
	v_add_u32_e32 v142, s6, v159
	v_ashrrev_i32_e32 v143, 31, v142
	v_lshlrev_b64 v[166:167], 11, v[142:143]
	v_lshl_add_u64 v[166:167], s[40:41], 0, v[166:167]
	s_andn2_b64 vcc, exec, s[24:25]
	v_lshl_add_u64 v[166:167], v[138:139], 1, v[166:167]
	s_waitcnt vmcnt(12)
	v_pk_add_f32 v[128:129], v[128:129], v[186:187]
	v_pk_add_f32 v[126:127], v[126:127], v[184:185]
	v_pk_add_f32 v[124:125], v[124:125], v[190:191]
	v_pk_add_f32 v[122:123], v[122:123], v[188:189]
	global_store_dwordx4 v[144:145], v[126:129], off
	global_store_dwordx4 v[144:145], v[122:125], off offset:16
	s_cbranch_vccnz .LBB0_1389
	v_cvt_pk_bf16_f32 v174, v126, v127
	v_cvt_pk_bf16_f32 v175, v128, v129
	v_cvt_pk_bf16_f32 v176, v122, v123
	v_cvt_pk_bf16_f32 v177, v124, v125
	global_store_dwordx4 v[166:167], v[174:177], off
.LBB0_1389:
	s_add_u32 s98, s26, 0x30000
	s_addc_u32 s99, s27, 0
	global_load_dwordx4 v[184:187], v202, s[98:99] offset:512
	global_load_dwordx4 v[188:191], v202, s[98:99] offset:528
	s_and_b64 vcc, exec, s[8:9]
	s_waitcnt vmcnt(14)
	v_pk_add_f32 v[120:121], v[120:121], v[194:195]
	v_pk_add_f32 v[118:119], v[118:119], v[192:193]
	v_pk_add_f32 v[116:117], v[116:117], v[198:199]
	v_pk_add_f32 v[114:115], v[114:115], v[196:197]
	global_store_dwordx4 v[144:145], v[118:121], off offset:512
	global_store_dwordx4 v[144:145], v[114:117], off offset:528
	s_cbranch_vccnz .LBB0_1391
	v_cvt_pk_bf16_f32 v174, v118, v119
	v_cvt_pk_bf16_f32 v175, v120, v121
	v_cvt_pk_bf16_f32 v176, v114, v115
	v_cvt_pk_bf16_f32 v177, v116, v117
	global_store_dwordx4 v[166:167], v[174:177], off offset:256

.LBB0_1395:
	v_or_b32_e32 v114, 16, v140
	s_waitcnt lgkmcnt(0)
	v_ashrrev_i32_e32 v115, 31, v114
	v_lshlrev_b64 v[116:117], 12, v[114:115]
	v_lshl_add_u64 v[116:117], s[26:27], 0, v[116:117]
	v_lshl_add_u64 v[116:117], v[138:139], 2, v[116:117]
	s_add_u32 s98, s26, 0x80000
	s_addc_u32 s99, s27, 0
	global_load_dwordx4 v[192:195], v202, s[98:99]
	global_load_dwordx4 v[196:199], v202, s[98:99] offset:16
	v_or_b32_e32 v126, 16, v142
	v_ashrrev_i32_e32 v127, 31, v126
	v_lshlrev_b64 v[126:127], 11, v[126:127]
	v_lshl_add_u64 v[126:127], s[40:41], 0, v[126:127]
	s_and_b64 vcc, exec, s[8:9]
	s_waitcnt vmcnt(16)
	v_pk_add_f32 v[112:113], v[112:113], v[214:215]
	v_pk_add_f32 v[110:111], v[110:111], v[212:213]
	v_pk_add_f32 v[108:109], v[108:109], v[218:219]
	v_pk_add_f32 v[106:107], v[106:107], v[216:217]
	v_lshl_add_u64 v[118:119], v[138:139], 1, v[126:127]
	global_store_dwordx4 v[116:117], v[110:113], off
	global_store_dwordx4 v[116:117], v[106:109], off offset:16
	s_cbranch_vccnz .LBB0_1397
	v_cvt_pk_bf16_f32 v120, v110, v111
	v_cvt_pk_bf16_f32 v121, v112, v113
	v_cvt_pk_bf16_f32 v122, v106, v107
	v_cvt_pk_bf16_f32 v123, v108, v109
	global_store_dwordx4 v[118:119], v[120:123], off
.LBB0_1397:
	s_add_u32 s98, s26, 0x80000
	s_addc_u32 s99, s27, 0
	global_load_dwordx4 v[212:215], v202, s[98:99] offset:512
	global_load_dwordx4 v[216:219], v202, s[98:99] offset:528
	s_and_b64 vcc, exec, s[8:9]
	s_waitcnt vmcnt(18)
	v_pk_add_f32 v[104:105], v[104:105], v[222:223]
	v_pk_add_f32 v[102:103], v[102:103], v[220:221]
	v_pk_add_f32 v[100:101], v[100:101], v[226:227]
	v_pk_add_f32 v[98:99], v[98:99], v[224:225]
	global_store_dwordx4 v[116:117], v[102:105], off offset:512
	global_store_dwordx4 v[116:117], v[98:101], off offset:528
	s_cbranch_vccnz .LBB0_1399
	v_cvt_pk_bf16_f32 v120, v102, v103
	v_cvt_pk_bf16_f32 v121, v104, v105
	v_cvt_pk_bf16_f32 v122, v98, v99
	v_cvt_pk_bf16_f32 v123, v100, v101
	global_store_dwordx4 v[118:119], v[120:123], off offset:256

.LBB0_1403:
	v_or_b32_e32 v98, 32, v140
	s_waitcnt lgkmcnt(0)
	v_ashrrev_i32_e32 v99, 31, v98
	v_lshlrev_b64 v[100:101], 12, v[98:99]
	v_lshl_add_u64 v[100:101], s[26:27], 0, v[100:101]
	v_lshl_add_u64 v[100:101], v[138:139], 2, v[100:101]
	s_add_u32 s98, s26, 0x90000
	s_addc_u32 s99, s27, 0
	global_load_dwordx4 v[220:223], v202, s[98:99]
	global_load_dwordx4 v[224:227], v202, s[98:99] offset:16
	v_or_b32_e32 v110, 32, v142
	v_ashrrev_i32_e32 v111, 31, v110
	v_lshlrev_b64 v[110:111], 11, v[110:111]
	v_lshl_add_u64 v[110:111], s[40:41], 0, v[110:111]
	s_and_b64 vcc, exec, s[8:9]
	s_waitcnt vmcnt(20)
	v_pk_add_f32 v[96:97], v[96:97], v[230:231]
	v_pk_add_f32 v[94:95], v[94:95], v[228:229]
	v_pk_add_f32 v[92:93], v[92:93], v[234:235]
	v_pk_add_f32 v[90:91], v[90:91], v[232:233]
	v_lshl_add_u64 v[102:103], v[138:139], 1, v[110:111]
	global_store_dwordx4 v[100:101], v[94:97], off
	global_store_dwordx4 v[100:101], v[90:93], off offset:16
	s_cbranch_vccnz .LBB0_1405
	v_cvt_pk_bf16_f32 v104, v94, v95
	v_cvt_pk_bf16_f32 v105, v96, v97
	v_cvt_pk_bf16_f32 v106, v90, v91
	v_cvt_pk_bf16_f32 v107, v92, v93
	global_store_dwordx4 v[102:103], v[104:107], off
.LBB0_1405:
	s_add_u32 s98, s26, 0x90000
	s_addc_u32 s99, s27, 0
	global_load_dwordx4 v[228:231], v202, s[98:99] offset:512
	global_load_dwordx4 v[232:235], v202, s[98:99] offset:528
	s_and_b64 vcc, exec, s[8:9]
	s_waitcnt vmcnt(22)
	v_pk_add_f32 v[88:89], v[88:89], v[238:239]
	v_pk_add_f32 v[86:87], v[86:87], v[236:237]
	v_pk_add_f32 v[84:85], v[84:85], v[242:243]
	v_pk_add_f32 v[82:83], v[82:83], v[240:241]
	global_store_dwordx4 v[100:101], v[86:89], off offset:512
	global_store_dwordx4 v[100:101], v[82:85], off offset:528
	s_cbranch_vccnz .LBB0_1407
	v_cvt_pk_bf16_f32 v104, v86, v87
	v_cvt_pk_bf16_f32 v105, v88, v89
	v_cvt_pk_bf16_f32 v106, v82, v83
	v_cvt_pk_bf16_f32 v107, v84, v85
	global_store_dwordx4 v[102:103], v[104:107], off offset:256

.LBB0_1411:
	v_or_b32_e32 v82, 48, v140
	s_waitcnt lgkmcnt(0)
	v_ashrrev_i32_e32 v83, 31, v82
	v_lshlrev_b64 v[84:85], 12, v[82:83]
	v_lshl_add_u64 v[84:85], s[26:27], 0, v[84:85]
	v_lshl_add_u64 v[84:85], v[138:139], 2, v[84:85]
	s_add_u32 s98, s26, 0xa0000
	s_addc_u32 s99, s27, 0
	global_load_dwordx4 v[236:239], v202, s[98:99]
	global_load_dwordx4 v[240:243], v202, s[98:99] offset:16
	v_or_b32_e32 v94, 48, v142
	v_ashrrev_i32_e32 v95, 31, v94
	v_lshlrev_b64 v[94:95], 11, v[94:95]
	v_lshl_add_u64 v[94:95], s[40:41], 0, v[94:95]
	s_and_b64 vcc, exec, s[8:9]
	s_waitcnt vmcnt(24)
	v_pk_add_f32 v[80:81], v[80:81], v[246:247]
	v_pk_add_f32 v[78:79], v[78:79], v[244:245]
	v_pk_add_f32 v[76:77], v[76:77], v[250:251]
	v_pk_add_f32 v[74:75], v[74:75], v[248:249]
	v_lshl_add_u64 v[86:87], v[138:139], 1, v[94:95]
	global_store_dwordx4 v[84:85], v[78:81], off
	global_store_dwordx4 v[84:85], v[74:77], off offset:16
	s_cbranch_vccnz .LBB0_1413
	v_cvt_pk_bf16_f32 v88, v78, v79
	v_cvt_pk_bf16_f32 v89, v80, v81
	v_cvt_pk_bf16_f32 v90, v74, v75
	v_cvt_pk_bf16_f32 v91, v76, v77
	global_store_dwordx4 v[86:87], v[88:91], off
.LBB0_1413:
	s_add_u32 s98, s26, 0xa0000
	s_addc_u32 s99, s27, 0
	global_load_dwordx4 v[244:247], v202, s[98:99] offset:512
	global_load_dwordx4 v[248:251], v202, s[98:99] offset:528
	s_and_b64 vcc, exec, s[8:9]
	s_waitcnt vmcnt(24)
	v_pk_add_f32 v[72:73], v[72:73], v[186:187]
	v_pk_add_f32 v[70:71], v[70:71], v[184:185]
	v_pk_add_f32 v[68:69], v[68:69], v[190:191]
	v_pk_add_f32 v[66:67], v[66:67], v[188:189]
	global_store_dwordx4 v[84:85], v[70:73], off offset:512
	global_store_dwordx4 v[84:85], v[66:69], off offset:528
	s_cbranch_vccnz .LBB0_1415
	v_cvt_pk_bf16_f32 v88, v70, v71
	v_cvt_pk_bf16_f32 v89, v72, v73
	v_cvt_pk_bf16_f32 v90, v66, v67
	v_cvt_pk_bf16_f32 v91, v68, v69
	global_store_dwordx4 v[86:87], v[88:91], off offset:256

.LBB0_1419:
	v_add_u32_e32 v66, 0x80, v140
	s_waitcnt lgkmcnt(0)
	v_ashrrev_i32_e32 v67, 31, v66
	v_lshlrev_b64 v[68:69], 12, v[66:67]
	v_lshl_add_u64 v[68:69], s[26:27], 0, v[68:69]
	v_lshl_add_u64 v[68:69], v[138:139], 2, v[68:69]
	s_add_u32 s98, s26, 0xb0000
	s_addc_u32 s99, s27, 0
	global_load_dwordx4 v[184:187], v202, s[98:99]
	global_load_dwordx4 v[188:191], v202, s[98:99] offset:16
	v_lshlrev_b64 v[78:79], 11, v[142:143]
	s_mov_b64 s[6:7], 0x40000
	v_lshl_add_u64 v[78:79], v[78:79], 0, s[6:7]
	v_lshl_add_u64 v[78:79], s[40:41], 0, v[78:79]
	s_and_b64 vcc, exec, s[8:9]
	s_waitcnt vmcnt(24)
	v_pk_add_f32 v[64:65], v[64:65], v[194:195]
	v_pk_add_f32 v[62:63], v[62:63], v[192:193]
	v_pk_add_f32 v[60:61], v[60:61], v[198:199]
	v_pk_add_f32 v[58:59], v[58:59], v[196:197]
	v_lshl_add_u64 v[70:71], v[138:139], 1, v[78:79]
	global_store_dwordx4 v[68:69], v[62:65], off
	global_store_dwordx4 v[68:69], v[58:61], off offset:16
	s_cbranch_vccnz .LBB0_1421
	v_cvt_pk_bf16_f32 v72, v62, v63
	v_cvt_pk_bf16_f32 v73, v64, v65
	v_cvt_pk_bf16_f32 v74, v58, v59
	v_cvt_pk_bf16_f32 v75, v60, v61
	global_store_dwordx4 v[70:71], v[72:75], off
.LBB0_1421:
	s_add_u32 s98, s26, 0xb0000
	s_addc_u32 s99, s27, 0
	global_load_dwordx4 v[192:195], v202, s[98:99] offset:512
	global_load_dwordx4 v[196:199], v202, s[98:99] offset:528
	s_and_b64 vcc, exec, s[8:9]
	s_waitcnt vmcnt(24)
	v_pk_add_f32 v[56:57], v[56:57], v[214:215]
	v_pk_add_f32 v[54:55], v[54:55], v[212:213]
	v_pk_add_f32 v[52:53], v[52:53], v[218:219]
	v_pk_add_f32 v[50:51], v[50:51], v[216:217]
	global_store_dwordx4 v[68:69], v[54:57], off offset:512
	global_store_dwordx4 v[68:69], v[50:53], off offset:528
	s_cbranch_vccnz .LBB0_1423
	v_cvt_pk_bf16_f32 v72, v54, v55
	v_cvt_pk_bf16_f32 v73, v56, v57
	v_cvt_pk_bf16_f32 v74, v50, v51
	v_cvt_pk_bf16_f32 v75, v52, v53
	global_store_dwordx4 v[70:71], v[72:75], off offset:256

.LBB0_1427:
	v_add_u32_e32 v50, 0x90, v140
	s_waitcnt lgkmcnt(0)
	v_ashrrev_i32_e32 v51, 31, v50
	v_lshlrev_b64 v[52:53], 12, v[50:51]
	v_lshl_add_u64 v[52:53], s[26:27], 0, v[52:53]
	v_lshl_add_u64 v[52:53], v[138:139], 2, v[52:53]
	v_lshlrev_b64 v[62:63], 11, v[142:143]
	v_lshl_add_u64 v[62:63], v[62:63], 0, s[58:59]
	v_lshl_add_u64 v[62:63], s[40:41], 0, v[62:63]
	s_and_b64 vcc, exec, s[8:9]
	s_waitcnt vmcnt(22)
	v_pk_add_f32 v[48:49], v[48:49], v[222:223]
	v_pk_add_f32 v[46:47], v[46:47], v[220:221]
	v_pk_add_f32 v[44:45], v[44:45], v[226:227]
	v_pk_add_f32 v[42:43], v[42:43], v[224:225]
	v_lshl_add_u64 v[54:55], v[138:139], 1, v[62:63]
	global_store_dwordx4 v[52:53], v[46:49], off
	global_store_dwordx4 v[52:53], v[42:45], off offset:16
	s_cbranch_vccnz .LBB0_1429
	v_cvt_pk_bf16_f32 v56, v46, v47
	v_cvt_pk_bf16_f32 v57, v48, v49
	v_cvt_pk_bf16_f32 v58, v42, v43
	v_cvt_pk_bf16_f32 v59, v44, v45
	global_store_dwordx4 v[54:55], v[56:59], off
.LBB0_1429:
	s_and_b64 vcc, exec, s[8:9]
	s_waitcnt vmcnt(20)
	v_pk_add_f32 v[40:41], v[40:41], v[230:231]
	v_pk_add_f32 v[38:39], v[38:39], v[228:229]
	v_pk_add_f32 v[36:37], v[36:37], v[234:235]
	v_pk_add_f32 v[34:35], v[34:35], v[232:233]
	global_store_dwordx4 v[52:53], v[38:41], off offset:512
	global_store_dwordx4 v[52:53], v[34:37], off offset:528
	s_cbranch_vccnz .LBB0_1431
	v_cvt_pk_bf16_f32 v56, v38, v39
	v_cvt_pk_bf16_f32 v57, v40, v41
	v_cvt_pk_bf16_f32 v58, v34, v35
	v_cvt_pk_bf16_f32 v59, v36, v37
	global_store_dwordx4 v[54:55], v[56:59], off offset:256

.LBB0_1435:
	v_add_u32_e32 v34, 0xa0, v140
	s_waitcnt lgkmcnt(0)
	v_ashrrev_i32_e32 v35, 31, v34
	v_lshlrev_b64 v[36:37], 12, v[34:35]
	v_lshl_add_u64 v[36:37], s[26:27], 0, v[36:37]
	v_lshl_add_u64 v[36:37], v[138:139], 2, v[36:37]
	v_lshlrev_b64 v[46:47], 11, v[142:143]
	v_lshl_add_u64 v[46:47], v[46:47], 0, s[60:61]
	v_lshl_add_u64 v[46:47], s[40:41], 0, v[46:47]
	s_and_b64 vcc, exec, s[8:9]
	s_waitcnt vmcnt(18)
	v_pk_add_f32 v[32:33], v[32:33], v[238:239]
	v_pk_add_f32 v[30:31], v[30:31], v[236:237]
	v_pk_add_f32 v[28:29], v[28:29], v[242:243]
	v_pk_add_f32 v[26:27], v[26:27], v[240:241]
	v_lshl_add_u64 v[38:39], v[138:139], 1, v[46:47]
	global_store_dwordx4 v[36:37], v[30:33], off
	global_store_dwordx4 v[36:37], v[26:29], off offset:16
	s_cbranch_vccnz .LBB0_1437
	v_cvt_pk_bf16_f32 v40, v30, v31
	v_cvt_pk_bf16_f32 v41, v32, v33
	v_cvt_pk_bf16_f32 v42, v26, v27
	v_cvt_pk_bf16_f32 v43, v28, v29
	global_store_dwordx4 v[38:39], v[40:43], off
.LBB0_1437:
	s_and_b64 vcc, exec, s[8:9]
	s_waitcnt vmcnt(16)
	v_pk_add_f32 v[24:25], v[24:25], v[246:247]
	v_pk_add_f32 v[22:23], v[22:23], v[244:245]
	v_pk_add_f32 v[20:21], v[20:21], v[250:251]
	v_pk_add_f32 v[18:19], v[18:19], v[248:249]
	global_store_dwordx4 v[36:37], v[22:25], off offset:512
	global_store_dwordx4 v[36:37], v[18:21], off offset:528
	s_cbranch_vccnz .LBB0_1439
	v_cvt_pk_bf16_f32 v40, v22, v23
	v_cvt_pk_bf16_f32 v41, v24, v25
	v_cvt_pk_bf16_f32 v42, v18, v19
	v_cvt_pk_bf16_f32 v43, v20, v21
	global_store_dwordx4 v[38:39], v[40:43], off offset:256

.LBB0_1443:
	v_add_u32_e32 v18, 0xb0, v140
	s_waitcnt lgkmcnt(0)
	v_ashrrev_i32_e32 v19, 31, v18
	v_lshlrev_b64 v[20:21], 12, v[18:19]
	v_lshl_add_u64 v[20:21], s[26:27], 0, v[20:21]
	v_lshl_add_u64 v[20:21], v[138:139], 2, v[20:21]
	v_lshlrev_b64 v[30:31], 11, v[142:143]
	v_lshl_add_u64 v[30:31], v[30:31], 0, s[62:63]
	v_lshl_add_u64 v[30:31], s[40:41], 0, v[30:31]
	s_and_b64 vcc, exec, s[8:9]
	s_waitcnt vmcnt(14)
	v_pk_add_f32 v[16:17], v[16:17], v[186:187]
	v_pk_add_f32 v[14:15], v[14:15], v[184:185]
	v_pk_add_f32 v[12:13], v[12:13], v[190:191]
	v_pk_add_f32 v[10:11], v[10:11], v[188:189]
	v_lshl_add_u64 v[22:23], v[138:139], 1, v[30:31]
	global_store_dwordx4 v[20:21], v[14:17], off
	global_store_dwordx4 v[20:21], v[10:13], off offset:16
	s_cbranch_vccnz .LBB0_1445
	v_cvt_pk_bf16_f32 v24, v14, v15
	v_cvt_pk_bf16_f32 v25, v16, v17
	v_cvt_pk_bf16_f32 v26, v10, v11
	v_cvt_pk_bf16_f32 v27, v12, v13
	global_store_dwordx4 v[22:23], v[24:27], off
.LBB0_1445:
	s_and_b64 vcc, exec, s[8:9]
	s_waitcnt vmcnt(12)
	v_pk_add_f32 v[8:9], v[8:9], v[194:195]
	v_pk_add_f32 v[6:7], v[6:7], v[192:193]
	v_pk_add_f32 v[4:5], v[4:5], v[198:199]
	v_pk_add_f32 v[2:3], v[2:3], v[196:197]
	global_store_dwordx4 v[20:21], v[6:9], off offset:512
	global_store_dwordx4 v[20:21], v[2:5], off offset:528
	s_cbranch_vccnz .LBB0_1447
	v_cvt_pk_bf16_f32 v24, v6, v7
	v_cvt_pk_bf16_f32 v25, v8, v9
	v_cvt_pk_bf16_f32 v26, v2, v3
	v_cvt_pk_bf16_f32 v27, v4, v5
	global_store_dwordx4 v[22:23], v[24:27], off offset:256

.LBB0_1652:
	v_lshl_add_u32 v140, s52, 8, v157
	v_ashrrev_i32_e32 v141, 31, v140
	v_lshl_or_b32 v138, s8, 8, v161
	v_lshlrev_b32_e32 v202, 12, v140
	v_lshl_add_u32 v202, v138, 2, v202
	v_lshlrev_b64 v[142:143], 12, v[140:141]
	v_ashrrev_i32_e32 v139, 31, v138
	v_lshl_add_u64 v[142:143], s[26:27], 0, v[142:143]
	v_lshl_add_u64 v[144:145], v[138:139], 2, v[142:143]
	s_add_u32 s98, s26, 0x0
	s_addc_u32 s99, s27, 0
	global_load_dwordx4 v[184:187], v202, s[98:99]
	global_load_dwordx4 v[188:191], v202, s[98:99] offset:16
	s_add_u32 s98, s26, 0x0
	s_addc_u32 s99, s27, 0
	global_load_dwordx4 v[192:195], v202, s[98:99] offset:512
	global_load_dwordx4 v[196:199], v202, s[98:99] offset:528
	s_add_u32 s98, s26, 0x10000
	s_addc_u32 s99, s27, 0
	global_load_dwordx4 v[212:215], v202, s[98:99]
	global_load_dwordx4 v[216:219], v202, s[98:99] offset:16
	s_add_u32 s98, s26, 0x10000
	s_addc_u32 s99, s27, 0
	global_load_dwordx4 v[220:223], v202, s[98:99] offset:512
	global_load_dwordx4 v[224:227], v202, s[98:99] offset:528
	s_add_u32 s98, s26, 0x20000
	s_addc_u32 s99, s27, 0
	global_load_dwordx4 v[228:231], v202, s[98:99]
	global_load_dwordx4 v[232:235], v202, s[98:99] offset:16
	s_add_u32 s98, s26, 0x20000
	s_addc_u32 s99, s27, 0
	global_load_dwordx4 v[236:239], v202, s[98:99] offset:512
	global_load_dwordx4 v[240:243], v202, s[98:99] offset:528
	s_add_u32 s98, s26, 0x30000
	s_addc_u32 s99, s27, 0
	global_load_dwordx4 v[244:247], v202, s[98:99]
	global_load_dwordx4 v[248:251], v202, s[98:99] offset:16
	s_cmp_lt_i32 s52, 32
	s_cselect_b32 s6, s69, 0xffffffd6
	v_cndmask_b32_e64 v142, 0, 1, s[22:23]
	s_add_i32 s6, s6, s52
	v_cmp_ne_u32_e64 s[8:9], 1, v142
	v_lshl_add_u32 v142, s6, 8, v157
	v_ashrrev_i32_e32 v143, 31, v142
	v_lshlrev_b64 v[164:165], 11, v[142:143]
	v_lshl_add_u64 v[164:165], s[40:41], 0, v[164:165]
	s_andn2_b64 vcc, exec, s[22:23]
	v_lshl_add_u64 v[164:165], v[138:139], 1, v[164:165]
	s_waitcnt vmcnt(12)
	v_pk_add_f32 v[128:129], v[128:129], v[186:187]
	v_pk_add_f32 v[126:127], v[126:127], v[184:185]
	v_pk_add_f32 v[124:125], v[124:125], v[190:191]
	v_pk_add_f32 v[122:123], v[122:123], v[188:189]
	global_store_dwordx4 v[144:145], v[126:129], off
	global_store_dwordx4 v[144:145], v[122:125], off offset:16
	s_cbranch_vccnz .LBB0_1654
	v_cvt_pk_bf16_f32 v174, v126, v127
	v_cvt_pk_bf16_f32 v175, v128, v129
	v_cvt_pk_bf16_f32 v176, v122, v123
	v_cvt_pk_bf16_f32 v177, v124, v125
	global_store_dwordx4 v[164:165], v[174:177], off
.LBB0_1654:
	s_add_u32 s98, s26, 0x30000
	s_addc_u32 s99, s27, 0
	global_load_dwordx4 v[184:187], v202, s[98:99] offset:512
	global_load_dwordx4 v[188:191], v202, s[98:99] offset:528
	s_and_b64 vcc, exec, s[8:9]
	s_waitcnt vmcnt(14)
	v_pk_add_f32 v[120:121], v[120:121], v[194:195]
	v_pk_add_f32 v[118:119], v[118:119], v[192:193]
	v_pk_add_f32 v[116:117], v[116:117], v[198:199]
	v_pk_add_f32 v[114:115], v[114:115], v[196:197]
	global_store_dwordx4 v[144:145], v[118:121], off offset:512
	global_store_dwordx4 v[144:145], v[114:117], off offset:528
	s_cbranch_vccnz .LBB0_1656
	v_cvt_pk_bf16_f32 v174, v118, v119
	v_cvt_pk_bf16_f32 v175, v120, v121
	v_cvt_pk_bf16_f32 v176, v114, v115
	v_cvt_pk_bf16_f32 v177, v116, v117
	global_store_dwordx4 v[164:165], v[174:177], off offset:256

.LBB0_1684:
	v_add_u32_e32 v66, 0x80, v140
	s_waitcnt lgkmcnt(0)
	v_ashrrev_i32_e32 v67, 31, v66
	v_lshlrev_b64 v[68:69], 12, v[66:67]
	v_lshl_add_u64 v[68:69], s[26:27], 0, v[68:69]
	v_lshl_add_u64 v[68:69], v[138:139], 2, v[68:69]
	s_add_u32 s98, s26, 0xb0000
	s_addc_u32 s99, s27, 0
	global_load_dwordx4 v[184:187], v202, s[98:99]
	global_load_dwordx4 v[188:191], v202, s[98:99] offset:16
	v_lshlrev_b64 v[78:79], 11, v[142:143]
	v_lshl_add_u64 v[78:79], v[78:79], 0, s[12:13]
	v_lshl_add_u64 v[78:79], s[40:41], 0, v[78:79]
	s_and_b64 vcc, exec, s[8:9]
	s_waitcnt vmcnt(24)
	v_pk_add_f32 v[64:65], v[64:65], v[194:195]
	v_pk_add_f32 v[62:63], v[62:63], v[192:193]
	v_pk_add_f32 v[60:61], v[60:61], v[198:199]
	v_pk_add_f32 v[58:59], v[58:59], v[196:197]
	v_lshl_add_u64 v[70:71], v[138:139], 1, v[78:79]
	global_store_dwordx4 v[68:69], v[62:65], off
	global_store_dwordx4 v[68:69], v[58:61], off offset:16
	s_cbranch_vccnz .LBB0_1686
	v_cvt_pk_bf16_f32 v72, v62, v63
	v_cvt_pk_bf16_f32 v73, v64, v65
	v_cvt_pk_bf16_f32 v74, v58, v59
	v_cvt_pk_bf16_f32 v75, v60, v61
	global_store_dwordx4 v[70:71], v[72:75], off

.LBB0_1692:
	v_add_u32_e32 v50, 0x90, v140
	s_waitcnt lgkmcnt(0)
	v_ashrrev_i32_e32 v51, 31, v50
	v_lshlrev_b64 v[52:53], 12, v[50:51]
	v_lshl_add_u64 v[52:53], s[26:27], 0, v[52:53]
	v_lshl_add_u64 v[52:53], v[138:139], 2, v[52:53]
	v_lshlrev_b64 v[62:63], 11, v[142:143]
	v_lshl_add_u64 v[62:63], v[62:63], 0, s[24:25]
	v_lshl_add_u64 v[62:63], s[40:41], 0, v[62:63]
	s_and_b64 vcc, exec, s[8:9]
	s_waitcnt vmcnt(22)
	v_pk_add_f32 v[48:49], v[48:49], v[222:223]
	v_pk_add_f32 v[46:47], v[46:47], v[220:221]
	v_pk_add_f32 v[44:45], v[44:45], v[226:227]
	v_pk_add_f32 v[42:43], v[42:43], v[224:225]
	v_lshl_add_u64 v[54:55], v[138:139], 1, v[62:63]
	global_store_dwordx4 v[52:53], v[46:49], off
	global_store_dwordx4 v[52:53], v[42:45], off offset:16
	s_cbranch_vccnz .LBB0_1694
	v_cvt_pk_bf16_f32 v56, v46, v47
	v_cvt_pk_bf16_f32 v57, v48, v49
	v_cvt_pk_bf16_f32 v58, v42, v43
	v_cvt_pk_bf16_f32 v59, v44, v45
	global_store_dwordx4 v[54:55], v[56:59], off

.LBB0_1700:
	v_add_u32_e32 v34, 0xa0, v140
	s_waitcnt lgkmcnt(0)
	v_ashrrev_i32_e32 v35, 31, v34
	v_lshlrev_b64 v[36:37], 12, v[34:35]
	v_lshl_add_u64 v[36:37], s[26:27], 0, v[36:37]
	v_lshl_add_u64 v[36:37], v[138:139], 2, v[36:37]
	v_lshlrev_b64 v[46:47], 11, v[142:143]
	v_lshl_add_u64 v[46:47], v[46:47], 0, s[34:35]
	v_lshl_add_u64 v[46:47], s[40:41], 0, v[46:47]
	s_and_b64 vcc, exec, s[8:9]
	s_waitcnt vmcnt(18)
	v_pk_add_f32 v[32:33], v[32:33], v[238:239]
	v_pk_add_f32 v[30:31], v[30:31], v[236:237]
	v_pk_add_f32 v[28:29], v[28:29], v[242:243]
	v_pk_add_f32 v[26:27], v[26:27], v[240:241]
	v_lshl_add_u64 v[38:39], v[138:139], 1, v[46:47]
	global_store_dwordx4 v[36:37], v[30:33], off
	global_store_dwordx4 v[36:37], v[26:29], off offset:16
	s_cbranch_vccnz .LBB0_1702
	v_cvt_pk_bf16_f32 v40, v30, v31
	v_cvt_pk_bf16_f32 v41, v32, v33
	v_cvt_pk_bf16_f32 v42, v26, v27
	v_cvt_pk_bf16_f32 v43, v28, v29
	global_store_dwordx4 v[38:39], v[40:43], off

.LBB0_1708:
	v_add_u32_e32 v18, 0xb0, v140
	s_waitcnt lgkmcnt(0)
	v_ashrrev_i32_e32 v19, 31, v18
	v_lshlrev_b64 v[20:21], 12, v[18:19]
	v_lshl_add_u64 v[20:21], s[26:27], 0, v[20:21]
	v_lshl_add_u64 v[20:21], v[138:139], 2, v[20:21]
	v_lshlrev_b64 v[30:31], 11, v[142:143]
	v_lshl_add_u64 v[30:31], v[30:31], 0, s[38:39]
	v_lshl_add_u64 v[30:31], s[40:41], 0, v[30:31]
	s_and_b64 vcc, exec, s[8:9]
	s_waitcnt vmcnt(14)
	v_pk_add_f32 v[16:17], v[16:17], v[186:187]
	v_pk_add_f32 v[14:15], v[14:15], v[184:185]
	v_pk_add_f32 v[12:13], v[12:13], v[190:191]
	v_pk_add_f32 v[10:11], v[10:11], v[188:189]
	v_lshl_add_u64 v[22:23], v[138:139], 1, v[30:31]
	global_store_dwordx4 v[20:21], v[14:17], off
	global_store_dwordx4 v[20:21], v[10:13], off offset:16
	s_cbranch_vccnz .LBB0_1710
	v_cvt_pk_bf16_f32 v24, v14, v15
	v_cvt_pk_bf16_f32 v25, v16, v17
	v_cvt_pk_bf16_f32 v26, v10, v11
	v_cvt_pk_bf16_f32 v27, v12, v13
	global_store_dwordx4 v[22:23], v[24:27], off
